# v37 + code placement: the 10 GEMM K-loop heads aligned to 64 bytes (.p2align 6), attention kv-loop heads at 0 mod 8
# baseline (speedup 1.0000x reference)
; template <class Epi>
; __device__ __forceinline__ void gemm_phase(LAS unsigned char* lds, int wave_s, const Gemm g, const StaticOrder S, const Epi E) {
;     ...
;         const bool has_next = S.next(ui + 1, nxt);
;         const char* nA = has_next ? (const char*)g.A + (size_t)nxt.pm * tstepA : cA; const char* nB = has_next ? (const char*)g.Bt + (size_t)nxt.pn * tstepB : cB;
;         for (int t = 0; t < nt; t += 2) {
;             const bool last = (t == nt - 2);
;             const char* a1 = cA + (size_t)(t + 1) * kstep;
;             const char* a2 = last ? nA : cA + (size_t)(t + 2) * kstep; const char* b2 = last ? nB : cB + (size_t)(t + 2) * kstep;
;     ...
; #pragma unroll
;         for (int a = 0; a < 2; ++a)
; #pragma unroll
;             for (int b = 0; b < 2; ++b)
; #pragma unroll
;                 for (int m = 0; m < 4; ++m)
; #pragma unroll
;                     for (int n = 0; n < 2; ++n) acc[a][b][m][n] = (f32x4){0.f, 0.f, 0.f, 0.f};
.LBB0_164:
	s_ashr_i32 s19, s18, 31
	s_lshl_b64 s[6:7], s[18:19], 19
	s_add_u32 s20, s38, s6
	s_addc_u32 s21, s39, s7
	s_and_b64 s[6:7], s[0:1], exec
	s_cselect_b32 s19, s21, s25
	s_cselect_b32 s45, s20, s24
	s_ashr_i32 s17, s16, 31
	s_lshl_b64 s[6:7], s[16:17], 19
	v_readlane_b32 s10, v252, 43
	v_readlane_b32 s11, v252, 44
	s_add_u32 s22, s10, s6
	s_addc_u32 s23, s11, s7
	s_and_b64 s[6:7], s[0:1], exec
	s_cselect_b32 s10, s23, s27
	s_cselect_b32 s11, s22, s26
	s_add_u32 s24, s24, 0x40080
	s_addc_u32 s25, s25, 0
	s_add_u32 s17, s26, 0x100
	v_mov_b32_e32 v2, 0
	s_addc_u32 s46, s27, 0
	s_mov_b32 s47, -2
	v_mov_b32_e32 v246, v2
	v_mov_b32_e32 v247, v2
	v_mov_b32_e32 v248, v2
	v_mov_b32_e32 v249, v2
	v_mov_b32_e32 v3, v2
	v_mov_b32_e32 v4, v2
	v_mfma_f32_32x32x16_bf16 v[18:33], v[246:249], v[246:249], 0
	v_mov_b32_e32 v5, v2
	v_mov_b32_e32 v6, v2
	v_mfma_f32_32x32x16_bf16 v[34:49], v[246:249], v[246:249], 0
	v_mov_b32_e32 v7, v2
	v_mov_b32_e32 v8, v2
	v_mfma_f32_32x32x16_bf16 v[50:65], v[246:249], v[246:249], 0
	v_mov_b32_e32 v9, v2
	v_mov_b32_e32 v10, v2
	v_mfma_f32_32x32x16_bf16 v[66:81], v[246:249], v[246:249], 0
	v_mov_b32_e32 v11, v2
	v_mov_b32_e32 v12, v2
	v_mfma_f32_32x32x16_bf16 v[82:97], v[246:249], v[246:249], 0
	v_mov_b32_e32 v13, v2
	v_mov_b32_e32 v14, v2
	v_mfma_f32_32x32x16_bf16 v[98:113], v[246:249], v[246:249], 0
	v_mov_b32_e32 v15, v2
	v_mov_b32_e32 v16, v2
	v_mfma_f32_32x32x16_bf16 v[114:129], v[246:249], v[246:249], 0
	v_mov_b32_e32 v17, v2
	.p2align 6

; template <class Epi>
; __device__ __forceinline__ void gemm_phase(LAS unsigned char* lds, int wave_s, const Gemm g, const StaticOrder S, const Epi E) {
;     ...
;         for (int t = 0; t < nt; t += 2) {
;             const bool last = (t == nt - 2);
;             const char* a1 = cA + (size_t)(t + 1) * kstep;
;             const char* a2 = last ? nA : cA + (size_t)(t + 2) * kstep; const char* b2 = last ? nB : cB + (size_t)(t + 2) * kstep;
;     ...
; #pragma unroll
;         for (int a = 0; a < 2; ++a)
; #pragma unroll
;             for (int b = 0; b < 2; ++b)
; #pragma unroll
;                 for (int m = 0; m < 4; ++m)
; #pragma unroll
;                     for (int n = 0; n < 2; ++n) acc[a][b][m][n] = (f32x4){0.f, 0.f, 0.f, 0.f};
.LBB0_240:
	s_add_u32 s10, s14, 0x100
	v_mov_b32_e32 v2, 0
	s_addc_u32 s11, s15, 0
	s_mov_b32 s34, -2
	v_mov_b32_e32 v246, v2
	v_mov_b32_e32 v247, v2
	v_mov_b32_e32 v248, v2
	v_mov_b32_e32 v249, v2
	v_mov_b32_e32 v3, v2
	v_mov_b32_e32 v4, v2
	v_mfma_f32_32x32x16_bf16 v[18:33], v[246:249], v[246:249], 0
	v_mov_b32_e32 v5, v2
	v_mov_b32_e32 v6, v2
	v_mfma_f32_32x32x16_bf16 v[34:49], v[246:249], v[246:249], 0
	v_mov_b32_e32 v7, v2
	v_mov_b32_e32 v8, v2
	v_mfma_f32_32x32x16_bf16 v[50:65], v[246:249], v[246:249], 0
	v_mov_b32_e32 v9, v2
	v_mov_b32_e32 v10, v2
	v_mfma_f32_32x32x16_bf16 v[66:81], v[246:249], v[246:249], 0
	v_mov_b32_e32 v11, v2
	v_mov_b32_e32 v12, v2
	v_mfma_f32_32x32x16_bf16 v[82:97], v[246:249], v[246:249], 0
	v_mov_b32_e32 v13, v2
	v_mov_b32_e32 v14, v2
	v_mfma_f32_32x32x16_bf16 v[98:113], v[246:249], v[246:249], 0
	v_mov_b32_e32 v15, v2
	v_mov_b32_e32 v16, v2
	v_mfma_f32_32x32x16_bf16 v[114:129], v[246:249], v[246:249], 0
	v_mov_b32_e32 v17, v2
	.p2align 6

; template <class Epi>
; __device__ __forceinline__ void gemm_phase(LAS unsigned char* lds, int wave_s, const Gemm g, const StaticOrder S, const Epi E) {
;     ...
;         const bool has_next = S.next(ui + 1, nxt);
;         const char* nA = has_next ? (const char*)g.A + (size_t)nxt.pm * tstepA : cA; const char* nB = has_next ? (const char*)g.Bt + (size_t)nxt.pn * tstepB : cB;
;         for (int t = 0; t < nt; t += 2) {
;             const bool last = (t == nt - 2);
;             const char* a1 = cA + (size_t)(t + 1) * kstep;
;             const char* a2 = last ? nA : cA + (size_t)(t + 2) * kstep; const char* b2 = last ? nB : cB + (size_t)(t + 2) * kstep;
;     ...
; #pragma unroll
;         for (int a = 0; a < 2; ++a)
; #pragma unroll
;             for (int b = 0; b < 2; ++b)
; #pragma unroll
;                 for (int m = 0; m < 4; ++m)
; #pragma unroll
;                     for (int n = 0; n < 2; ++n) acc[a][b][m][n] = (f32x4){0.f, 0.f, 0.f, 0.f};
.LBB0_327:
	s_ashr_i32 s23, s22, 31
	s_lshl_b64 s[6:7], s[22:23], 19
	s_add_u32 s24, s50, s6
	s_addc_u32 s25, s51, s7
	s_and_b64 s[6:7], s[48:49], exec
	s_cselect_b32 s23, s25, s1
	s_cselect_b32 s34, s24, s0
	s_ashr_i32 s21, s20, 31
	s_lshl_b64 s[6:7], s[20:21], 19
	v_readlane_b32 s10, v250, 33
	v_readlane_b32 s11, v250, 34
	s_add_u32 s26, s10, s6
	s_addc_u32 s27, s11, s7
	s_and_b64 s[6:7], s[48:49], exec
	s_cselect_b32 s10, s27, s29
	s_cselect_b32 s11, s26, s28
	s_add_u32 s0, s0, 0x40080
	s_addc_u32 s1, s1, 0
	s_add_u32 s21, s28, 0x100
	v_mov_b32_e32 v2, 0
	s_addc_u32 s35, s29, 0
	s_mov_b32 s50, -2
	v_mov_b32_e32 v3, v2
	v_mov_b32_e32 v4, v2
	v_mov_b32_e32 v5, v2
	v_mov_b32_e32 v6, v2
	v_mov_b32_e32 v7, v2
	v_mov_b32_e32 v8, v2
	v_mov_b32_e32 v9, v2
	v_mov_b32_e32 v10, v2
	s_waitcnt lgkmcnt(0)
	v_mov_b32_e32 v246, v2
	v_mov_b32_e32 v247, v2
	v_mov_b32_e32 v248, v2
	v_mov_b32_e32 v249, v2
	v_mov_b32_e32 v11, v2
	v_mov_b32_e32 v12, v2
	v_mfma_f32_32x32x16_bf16 v[18:33], v[246:249], v[246:249], 0
	v_mov_b32_e32 v13, v2
	v_mov_b32_e32 v14, v2
	v_mfma_f32_32x32x16_bf16 v[34:49], v[246:249], v[246:249], 0
	v_mov_b32_e32 v15, v2
	v_mov_b32_e32 v16, v2
	v_mfma_f32_32x32x16_bf16 v[50:65], v[246:249], v[246:249], 0
	v_mov_b32_e32 v17, v2
	v_mfma_f32_32x32x16_bf16 v[66:81], v[246:249], v[246:249], 0
	v_mfma_f32_32x32x16_bf16 v[82:97], v[246:249], v[246:249], 0
	v_mfma_f32_32x32x16_bf16 v[98:113], v[246:249], v[246:249], 0
	v_mfma_f32_32x32x16_bf16 v[114:129], v[246:249], v[246:249], 0
	.p2align 6

; template <class Epi>
; __device__ __forceinline__ void gemm_phase(LAS unsigned char* lds, int wave_s, const Gemm g, const StaticOrder S, const Epi E) {
;     ...
;         for (int t = 0; t < nt; t += 2) {
;             const bool last = (t == nt - 2);
;             const char* a1 = cA + (size_t)(t + 1) * kstep;
;             const char* a2 = last ? nA : cA + (size_t)(t + 2) * kstep; const char* b2 = last ? nB : cB + (size_t)(t + 2) * kstep;
;     ...
; #pragma unroll
;         for (int a = 0; a < 2; ++a)
; #pragma unroll
;             for (int b = 0; b < 2; ++b)
; #pragma unroll
;                 for (int m = 0; m < 4; ++m)
; #pragma unroll
;                     for (int n = 0; n < 2; ++n) acc[a][b][m][n] = (f32x4){0.f, 0.f, 0.f, 0.f};
.LBB0_564:
	s_add_u32 s10, s20, 0x100
	v_mov_b32_e32 v2, 0
	s_addc_u32 s11, s21, 0
	s_mov_b32 s50, -2
	v_mov_b32_e32 v246, v2
	v_mov_b32_e32 v247, v2
	v_mov_b32_e32 v248, v2
	v_mov_b32_e32 v249, v2
	v_mov_b32_e32 v3, v2
	v_mov_b32_e32 v4, v2
	v_mfma_f32_32x32x16_bf16 v[18:33], v[246:249], v[246:249], 0
	v_mov_b32_e32 v5, v2
	v_mov_b32_e32 v6, v2
	v_mfma_f32_32x32x16_bf16 v[34:49], v[246:249], v[246:249], 0
	v_mov_b32_e32 v7, v2
	v_mov_b32_e32 v8, v2
	v_mfma_f32_32x32x16_bf16 v[50:65], v[246:249], v[246:249], 0
	v_mov_b32_e32 v9, v2
	v_mov_b32_e32 v10, v2
	v_mfma_f32_32x32x16_bf16 v[66:81], v[246:249], v[246:249], 0
	v_mov_b32_e32 v11, v2
	v_mov_b32_e32 v12, v2
	v_mfma_f32_32x32x16_bf16 v[82:97], v[246:249], v[246:249], 0
	v_mov_b32_e32 v13, v2
	v_mov_b32_e32 v14, v2
	v_mfma_f32_32x32x16_bf16 v[98:113], v[246:249], v[246:249], 0
	v_mov_b32_e32 v15, v2
	v_mov_b32_e32 v16, v2
	v_mfma_f32_32x32x16_bf16 v[114:129], v[246:249], v[246:249], 0
	v_mov_b32_e32 v17, v2
	.p2align 6

; template <class Epi>
; __device__ __forceinline__ void gemm_phase(LAS unsigned char* lds, int wave_s, const Gemm g, const StaticOrder S, const Epi E) {
;     ...
;         const bool has_next = S.next(ui + 1, nxt);
;         const char* nA = has_next ? (const char*)g.A + (size_t)nxt.pm * tstepA : cA; const char* nB = has_next ? (const char*)g.Bt + (size_t)nxt.pn * tstepB : cB;
;         for (int t = 0; t < nt; t += 2) {
;             const bool last = (t == nt - 2);
;             const char* a1 = cA + (size_t)(t + 1) * kstep;
;             const char* a2 = last ? nA : cA + (size_t)(t + 2) * kstep; const char* b2 = last ? nB : cB + (size_t)(t + 2) * kstep;
;     ...
; #pragma unroll
;         for (int a = 0; a < 2; ++a)
; #pragma unroll
;             for (int b = 0; b < 2; ++b)
; #pragma unroll
;                 for (int m = 0; m < 4; ++m)
; #pragma unroll
;                     for (int n = 0; n < 2; ++n) acc[a][b][m][n] = (f32x4){0.f, 0.f, 0.f, 0.f};
.LBB0_634:
	s_ashr_i32 s17, s16, 31
	s_lshl_b64 s[6:7], s[16:17], 17
	v_readlane_b32 s10, v255, 55
	v_readlane_b32 s11, v255, 56
	s_add_u32 s20, s10, s6
	s_addc_u32 s21, s11, s7
	s_and_b64 s[0:1], s[0:1], exec
	v_mov_b32_e32 v2, 0
	s_cselect_b32 s17, s21, s23
	s_cselect_b32 s10, s20, s22
	s_mov_b32 s11, 0
	s_mov_b64 s[0:1], -1
	s_mov_b64 s[26:27], 0
	v_mov_b32_e32 v246, v2
	v_mov_b32_e32 v247, v2
	v_mov_b32_e32 v248, v2
	v_mov_b32_e32 v249, v2
	v_mov_b32_e32 v3, v2
	v_mov_b32_e32 v4, v2
	v_mfma_f32_32x32x16_bf16 v[18:33], v[246:249], v[246:249], 0
	v_mov_b32_e32 v5, v2
	v_mov_b32_e32 v6, v2
	v_mfma_f32_32x32x16_bf16 v[34:49], v[246:249], v[246:249], 0
	v_mov_b32_e32 v7, v2
	v_mov_b32_e32 v8, v2
	v_mfma_f32_32x32x16_bf16 v[50:65], v[246:249], v[246:249], 0
	v_mov_b32_e32 v9, v2
	v_mov_b32_e32 v10, v2
	v_mfma_f32_32x32x16_bf16 v[66:81], v[246:249], v[246:249], 0
	v_mov_b32_e32 v11, v2
	v_mov_b32_e32 v12, v2
	v_mfma_f32_32x32x16_bf16 v[82:97], v[246:249], v[246:249], 0
	v_mov_b32_e32 v13, v2
	v_mov_b32_e32 v14, v2
	v_mfma_f32_32x32x16_bf16 v[98:113], v[246:249], v[246:249], 0
	v_mov_b32_e32 v15, v2
	v_mov_b32_e32 v16, v2
	v_mfma_f32_32x32x16_bf16 v[114:129], v[246:249], v[246:249], 0
	v_mov_b32_e32 v17, v2
	.p2align 6

; template <class Epi>
; __device__ __forceinline__ void gemm_phase(LAS unsigned char* lds, int wave_s, const Gemm g, const StaticOrder S, const Epi E) {
;     ...
;         const bool has_next = S.next(ui + 1, nxt);
;         const char* nA = has_next ? (const char*)g.A + (size_t)nxt.pm * tstepA : cA; const char* nB = has_next ? (const char*)g.Bt + (size_t)nxt.pn * tstepB : cB;
;         for (int t = 0; t < nt; t += 2) {
;             const bool last = (t == nt - 2);
;             const char* a1 = cA + (size_t)(t + 1) * kstep;
;             const char* a2 = last ? nA : cA + (size_t)(t + 2) * kstep; const char* b2 = last ? nB : cB + (size_t)(t + 2) * kstep;
;     ...
; #pragma unroll
;         for (int a = 0; a < 2; ++a)
; #pragma unroll
;             for (int b = 0; b < 2; ++b)
; #pragma unroll
;                 for (int m = 0; m < 4; ++m)
; #pragma unroll
;                     for (int n = 0; n < 2; ++n) acc[a][b][m][n] = (f32x4){0.f, 0.f, 0.f, 0.f};
.LBB0_1067:
	s_ashr_i32 s21, s20, 31
	s_lshl_b64 s[6:7], s[20:21], 19
	v_readlane_b32 s10, v253, 6
	v_readlane_b32 s11, v253, 7
	s_add_u32 s24, s10, s6
	s_addc_u32 s25, s11, s7
	s_and_b64 s[0:1], s[0:1], exec
	s_cselect_b32 s10, s25, s29
	s_cselect_b32 s11, s24, s28
	s_add_u32 s21, s28, 0x100
	v_mov_b32_e32 v2, 0
	s_addc_u32 s52, s29, 0
	s_mov_b32 s53, -2
	v_mov_b32_e32 v246, v2
	v_mov_b32_e32 v247, v2
	v_mov_b32_e32 v248, v2
	v_mov_b32_e32 v249, v2
	v_mov_b32_e32 v3, v2
	v_mov_b32_e32 v4, v2
	v_mfma_f32_32x32x16_bf16 v[18:33], v[246:249], v[246:249], 0
	v_mov_b32_e32 v5, v2
	v_mov_b32_e32 v6, v2
	v_mfma_f32_32x32x16_bf16 v[34:49], v[246:249], v[246:249], 0
	v_mov_b32_e32 v7, v2
	v_mov_b32_e32 v8, v2
	v_mfma_f32_32x32x16_bf16 v[50:65], v[246:249], v[246:249], 0
	v_mov_b32_e32 v9, v2
	v_mov_b32_e32 v10, v2
	v_mfma_f32_32x32x16_bf16 v[66:81], v[246:249], v[246:249], 0
	v_mov_b32_e32 v11, v2
	v_mov_b32_e32 v12, v2
	v_mfma_f32_32x32x16_bf16 v[82:97], v[246:249], v[246:249], 0
	v_mov_b32_e32 v13, v2
	v_mov_b32_e32 v14, v2
	v_mfma_f32_32x32x16_bf16 v[98:113], v[246:249], v[246:249], 0
	v_mov_b32_e32 v15, v2
	v_mov_b32_e32 v16, v2
	v_mfma_f32_32x32x16_bf16 v[114:129], v[246:249], v[246:249], 0
	v_mov_b32_e32 v17, v2
	.p2align 6

; template <class Epi>
; __device__ __forceinline__ void gemm_phase(LAS unsigned char* lds, int wave_s, const Gemm g, const StaticOrder S, const Epi E) {
;     ...
;         const bool has_next = S.next(ui + 1, nxt);
;         const char* nA = has_next ? (const char*)g.A + (size_t)nxt.pm * tstepA : cA; const char* nB = has_next ? (const char*)g.Bt + (size_t)nxt.pn * tstepB : cB;
;         for (int t = 0; t < nt; t += 2) {
;             const bool last = (t == nt - 2);
;             const char* a1 = cA + (size_t)(t + 1) * kstep;
;             const char* a2 = last ? nA : cA + (size_t)(t + 2) * kstep; const char* b2 = last ? nB : cB + (size_t)(t + 2) * kstep;
;     ...
; #pragma unroll
;         for (int a = 0; a < 2; ++a)
; #pragma unroll
;             for (int b = 0; b < 2; ++b)
; #pragma unroll
;                 for (int m = 0; m < 4; ++m)
; #pragma unroll
;                     for (int n = 0; n < 2; ++n) acc[a][b][m][n] = (f32x4){0.f, 0.f, 0.f, 0.f};
.LBB0_1150:
	s_ashr_i32 s17, s16, 31
	s_lshl_b64 s[6:7], s[16:17], 19
	v_readlane_b32 s10, v253, 35
	v_readlane_b32 s11, v253, 36
	s_add_u32 s18, s10, s6
	s_addc_u32 s19, s11, s7
	s_and_b64 s[6:7], s[42:43], exec
	s_cselect_b32 s17, s19, s23
	s_cselect_b32 s40, s18, s22
	s_ashr_i32 s15, s14, 31
	s_lshl_b64 s[6:7], s[14:15], 19
	v_readlane_b32 s10, v252, 54
	v_readlane_b32 s11, v252, 55
	s_add_u32 s20, s10, s6
	s_addc_u32 s21, s11, s7
	s_and_b64 s[6:7], s[42:43], exec
	s_cselect_b32 s10, s21, s25
	s_cselect_b32 s11, s20, s24
	s_add_u32 s22, s22, 0x40080
	s_addc_u32 s23, s23, 0
	s_add_u32 s15, s24, 0x100
	v_mov_b32_e32 v2, 0
	s_addc_u32 s44, s25, 0
	s_mov_b32 s45, -2
	v_mov_b32_e32 v246, v2
	v_mov_b32_e32 v247, v2
	v_mov_b32_e32 v248, v2
	v_mov_b32_e32 v249, v2
	v_mov_b32_e32 v3, v2
	v_mov_b32_e32 v4, v2
	v_mfma_f32_32x32x16_bf16 v[18:33], v[246:249], v[246:249], 0
	v_mov_b32_e32 v5, v2
	v_mov_b32_e32 v6, v2
	v_mfma_f32_32x32x16_bf16 v[34:49], v[246:249], v[246:249], 0
	v_mov_b32_e32 v7, v2
	v_mov_b32_e32 v8, v2
	v_mfma_f32_32x32x16_bf16 v[50:65], v[246:249], v[246:249], 0
	v_mov_b32_e32 v9, v2
	v_mov_b32_e32 v10, v2
	v_mfma_f32_32x32x16_bf16 v[66:81], v[246:249], v[246:249], 0
	v_mov_b32_e32 v11, v2
	v_mov_b32_e32 v12, v2
	v_mfma_f32_32x32x16_bf16 v[82:97], v[246:249], v[246:249], 0
	v_mov_b32_e32 v13, v2
	v_mov_b32_e32 v14, v2
	v_mfma_f32_32x32x16_bf16 v[98:113], v[246:249], v[246:249], 0
	v_mov_b32_e32 v15, v2
	v_mov_b32_e32 v16, v2
	v_mfma_f32_32x32x16_bf16 v[114:129], v[246:249], v[246:249], 0
	v_mov_b32_e32 v17, v2
	.p2align 6

; template <class Epi>
; __device__ __forceinline__ void gemm_phase(LAS unsigned char* lds, int wave_s, const Gemm g, const StaticOrder S, const Epi E) {
;     ...
;         const bool has_next = S.next(ui + 1, nxt);
;         const char* nA = has_next ? (const char*)g.A + (size_t)nxt.pm * tstepA : cA; const char* nB = has_next ? (const char*)g.Bt + (size_t)nxt.pn * tstepB : cB;
;         for (int t = 0; t < nt; t += 2) {
;             const bool last = (t == nt - 2);
;             const char* a1 = cA + (size_t)(t + 1) * kstep;
;             const char* a2 = last ? nA : cA + (size_t)(t + 2) * kstep; const char* b2 = last ? nB : cB + (size_t)(t + 2) * kstep;
;     ...
; #pragma unroll
;         for (int a = 0; a < 2; ++a)
; #pragma unroll
;             for (int b = 0; b < 2; ++b)
; #pragma unroll
;                 for (int m = 0; m < 4; ++m)
; #pragma unroll
;                     for (int n = 0; n < 2; ++n) acc[a][b][m][n] = (f32x4){0.f, 0.f, 0.f, 0.f};
.LBB0_1170:
	s_ashr_i32 s17, s16, 31
	s_lshl_b64 s[0:1], s[16:17], 17
	s_add_u32 s18, s20, s0
	s_addc_u32 s19, s21, s1
	s_and_b64 s[0:1], s[42:43], exec
	s_cselect_b32 s17, s19, s25
	s_cselect_b32 s56, s18, s24
	s_ashr_i32 s15, s14, 31
	s_lshl_b64 s[0:1], s[14:15], 17
	v_readlane_b32 s6, v255, 4
	v_readlane_b32 s7, v255, 5
	s_add_u32 s20, s6, s0
	s_addc_u32 s21, s7, s1
	s_and_b64 s[0:1], s[42:43], exec
	v_mov_b32_e32 v2, 0
	s_cselect_b32 s15, s21, s23
	s_cselect_b32 s10, s20, s22
	s_mov_b32 s11, 0
	s_mov_b64 s[26:27], -1
	s_mov_b64 s[28:29], 0
	v_mov_b32_e32 v246, v2
	v_mov_b32_e32 v247, v2
	v_mov_b32_e32 v248, v2
	v_mov_b32_e32 v249, v2
	v_mov_b32_e32 v3, v2
	v_mov_b32_e32 v4, v2
	v_mfma_f32_32x32x16_bf16 v[18:33], v[246:249], v[246:249], 0
	v_mov_b32_e32 v5, v2
	v_mov_b32_e32 v6, v2
	v_mfma_f32_32x32x16_bf16 v[34:49], v[246:249], v[246:249], 0
	v_mov_b32_e32 v7, v2
	v_mov_b32_e32 v8, v2
	v_mfma_f32_32x32x16_bf16 v[50:65], v[246:249], v[246:249], 0
	v_mov_b32_e32 v9, v2
	v_mov_b32_e32 v10, v2
	v_mfma_f32_32x32x16_bf16 v[66:81], v[246:249], v[246:249], 0
	v_mov_b32_e32 v11, v2
	v_mov_b32_e32 v12, v2
	v_mfma_f32_32x32x16_bf16 v[82:97], v[246:249], v[246:249], 0
	v_mov_b32_e32 v13, v2
	v_mov_b32_e32 v14, v2
	v_mfma_f32_32x32x16_bf16 v[98:113], v[246:249], v[246:249], 0
	v_mov_b32_e32 v15, v2
	v_mov_b32_e32 v16, v2
	v_mfma_f32_32x32x16_bf16 v[114:129], v[246:249], v[246:249], 0
	v_mov_b32_e32 v17, v2
	.p2align 6

; template <class Epi>
; __device__ __forceinline__ void gemm_phase(LAS unsigned char* lds, int wave_s, const Gemm g, const StaticOrder S, const Epi E) {
;     ...
;         const bool has_next = S.next(ui + 1, nxt);
;         const char* nA = has_next ? (const char*)g.A + (size_t)nxt.pm * tstepA : cA; const char* nB = has_next ? (const char*)g.Bt + (size_t)nxt.pn * tstepB : cB;
;         for (int t = 0; t < nt; t += 2) {
;             const bool last = (t == nt - 2);
;             const char* a1 = cA + (size_t)(t + 1) * kstep;
;             const char* a2 = last ? nA : cA + (size_t)(t + 2) * kstep; const char* b2 = last ? nB : cB + (size_t)(t + 2) * kstep;
;     ...
; #pragma unroll
;         for (int a = 0; a < 2; ++a)
; #pragma unroll
;             for (int b = 0; b < 2; ++b)
; #pragma unroll
;                 for (int m = 0; m < 4; ++m)
; #pragma unroll
;                     for (int n = 0; n < 2; ++n) acc[a][b][m][n] = (f32x4){0.f, 0.f, 0.f, 0.f};
.LBB0_1334:
	s_ashr_i32 s49, s48, 31
	s_lshl_b64 s[6:7], s[48:49], 19
	v_readlane_b32 s10, v253, 35
	v_readlane_b32 s11, v253, 36
	s_add_u32 s50, s10, s6
	s_addc_u32 s51, s11, s7
	s_and_b64 s[6:7], s[42:43], exec
	s_cselect_b32 s28, s51, s13
	s_cselect_b32 s29, s50, s12
	s_ashr_i32 s57, s56, 31
	s_lshl_b64 s[6:7], s[56:57], 19
	v_readlane_b32 s10, v253, 31
	v_readlane_b32 s11, v253, 32
	s_add_u32 s52, s10, s6
	s_addc_u32 s53, s11, s7
	s_and_b64 s[6:7], s[42:43], exec
	s_cselect_b32 s10, s53, s15
	s_cselect_b32 s11, s52, s14
	s_add_u32 s12, s12, 0x40080
	s_addc_u32 s13, s13, 0
	s_add_u32 s30, s14, 0x100
	v_mov_b32_e32 v2, 0
	s_addc_u32 s31, s15, 0
	s_mov_b32 s34, -2
	v_mov_b32_e32 v246, v2
	v_mov_b32_e32 v247, v2
	v_mov_b32_e32 v248, v2
	v_mov_b32_e32 v249, v2
	v_mov_b32_e32 v3, v2
	v_mov_b32_e32 v4, v2
	v_mfma_f32_32x32x16_bf16 v[18:33], v[246:249], v[246:249], 0
	v_mov_b32_e32 v5, v2
	v_mov_b32_e32 v6, v2
	v_mfma_f32_32x32x16_bf16 v[34:49], v[246:249], v[246:249], 0
	v_mov_b32_e32 v7, v2
	v_mov_b32_e32 v8, v2
	v_mfma_f32_32x32x16_bf16 v[50:65], v[246:249], v[246:249], 0
	v_mov_b32_e32 v9, v2
	v_mov_b32_e32 v10, v2
	v_mfma_f32_32x32x16_bf16 v[66:81], v[246:249], v[246:249], 0
	v_mov_b32_e32 v11, v2
	v_mov_b32_e32 v12, v2
	v_mfma_f32_32x32x16_bf16 v[82:97], v[246:249], v[246:249], 0
	v_mov_b32_e32 v13, v2
	v_mov_b32_e32 v14, v2
	v_mfma_f32_32x32x16_bf16 v[98:113], v[246:249], v[246:249], 0
	v_mov_b32_e32 v15, v2
	v_mov_b32_e32 v16, v2
	v_mfma_f32_32x32x16_bf16 v[114:129], v[246:249], v[246:249], 0
	v_mov_b32_e32 v17, v2
	.p2align 6
